# opt15
# baseline (speedup 1.0000x reference)
; __device__ __forceinline__ int opaque_tid() { int t = threadIdx.x; asm volatile("" : "+v"(t)); return t; }
; #define WAIT_V(n) asm volatile("s_waitcnt vmcnt(" #n ")" ::: "memory")
; #define BAR __builtin_amdgcn_s_barrier()
; template <bool PEEL = false>
; __device__ __forceinline__ void gemm_tile(f32x4 (&acc)[2][2][4][2], const u16* __restrict__ A, int lda,
;                                           const u16* __restrict__ B, int K) {
;     ...
;   const int tid = opaque_tid();
;   const int wid = tid >> 6, lane = tid & 63, wr = wid >> 2, wc = wid & 3, fr = lane & 15, fq = lane >> 4;
;   int rA0, rB0;
;   {
;     int r, c;
;     stage_rc(tid * 16, r, c);
;     rA0 = (r * lda + c) * 2; rB0 = (r * K + c) * 2;
;   }
;   const int wbase = __builtin_amdgcn_readfirstlane(wid) * 1024;
;   const __amdgpu_buffer_rsrc_t rsA = __builtin_amdgcn_make_buffer_rsrc((void*)A, 0, 0x40000000, 0x00020000);
;   const __amdgpu_buffer_rsrc_t rsB = __builtin_amdgcn_make_buffer_rsrc((void*)B, 0, 0x40000000, 0x00020000);
; #pragma unroll
;   for (int a = 0; a < 2; ++a)
; #pragma unroll
;     for (int b = 0; b < 2; ++b)
; #pragma unroll
;       for (int m = 0; m < 4; ++m)
; #pragma unroll
;         for (int n = 0; n < 2; ++n) acc[a][b][m][n] = f32x4{0.f, 0.f, 0.f, 0.f};
;   bf16x8 At[4][2], B0[2][2], B1[2][2];
;   const int nt = K / 64;
;   STAGE_B(SB(0, 0), 0, 0); STAGE_A(SA(0, 0), 0, 0);
;   STAGE_B(SB(0, 1), 1, 0); STAGE_A(SA(0, 1), 1, 0);
;   if (wr == 1) BAR;
;   WAIT_V(4); BAR;
;   STAGE_B(SB(1, 0), 0, 1); STAGE_A(SA(1, 0), 0, 1); STAGE_B(SB(1, 1), 1, 1);
;   WAIT_V(6); BAR;
.LBB0_150:
	v_mov_b32_e32 v128, v254
	s_lshl_b32 s4, s1, 6
	v_bfe_i32 v3, v128, 27, 1
	v_lshlrev_b32_e32 v1, 4, v128
	v_lshrrev_b32_e32 v3, 22, v3
	v_add_u32_e32 v3, v1, v3
	v_and_b32_e32 v3, 0xfffffc00, v3
	v_ashrrev_i32_e32 v2, 31, v128
	v_sub_u32_e32 v1, v1, v3
	v_lshrrev_b32_e32 v2, 26, v2
	v_lshrrev_b32_e32 v3, 4, v1
	v_add_u32_e32 v2, v128, v2
	v_bitop3_b32 v3, v3, v1, 32 bitop3:0x6c
	v_ashrrev_i32_e32 v1, 31, v1
	s_add_i32 s14, s4, s71
	v_ashrrev_i32_e32 v2, 6, v2
	v_lshrrev_b32_e32 v1, 26, v1
	s_ashr_i32 s15, s14, 31
	v_lshlrev_b32_e32 v4, 3, v2
	v_add_u32_e32 v1, v3, v1
	s_lshl_b64 s[4:5], s[14:15], 21
	v_ashrrev_i32_e32 v0, 6, v128
	v_and_b32_e32 v4, 0xfffff0, v4
	v_ashrrev_i32_e32 v1, 6, v1
	s_add_u32 s4, s33, s4
	v_add_u32_e32 v4, v1, v4
	v_mul_i32_i24_e32 v1, 64, v1
	v_readfirstlane_b32 s36, v0
	s_addc_u32 s5, s96, s5
	v_sub_u32_e32 v1, v3, v1
	s_movk_i32 s6, 0xb00
	s_lshl_b32 s67, s36, 10
	v_lshlrev_b32_e32 v2, 5, v2
	v_ashrrev_i16_sdwa v1, v172, sext(v1) dst_sel:DWORD dst_unused:UNUSED_PAD src0_sel:DWORD src1_sel:BYTE_0
	v_mul_lo_u32 v3, v4, s6
	s_add_i32 s36, s67, 0
	v_bfe_i32 v1, v1, 0, 16
	v_and_or_b32 v2, v2, 32, v3
	s_add_i32 s37, s36, 0x10000
	v_add_lshl_u32 v134, v2, v1, 1
	s_add_i32 s38, s36, 0x12000
	s_and_b32 s5, s5, 0xffff
	s_mov_b32 s6, s10
	s_mov_b32 s7, s11
	s_add_i32 s39, s36, 0x2000
	s_add_i32 s40, s36, 0x14000
	s_add_i32 s41, s36, 0x16000
	s_add_i32 s42, s36, 0x4000
	s_add_i32 s43, s36, 0x6000
	s_add_i32 s45, s97, s67
	s_add_i32 s46, s45, 0x2000
	s_add_i32 s47, s36, 0x8000
	s_add_i32 s78, s36, 0xa000
	s_add_i32 s82, s68, s67
	s_add_i32 s83, s82, 0x2000
	v_ashrrev_i32_e32 v1, 8, v128
	v_cmp_eq_u32_e32 vcc, 1, v1
	s_cmp_lg_u32 s1, 0
	s_cbranch_scc1 .Lpf5_hdr
	s_mov_b32 m0, s37
	s_nop 0
	buffer_load_dwordx4 v134, s[8:11], 0 offen lds
	s_mov_b32 m0, s38
	s_nop 0
	buffer_load_dwordx4 v134, s[8:11], s16 offen lds
	s_mov_b32 m0, s36
	s_nop 0
	buffer_load_dwordx4 v134, s[4:7], 0 offen lds
	s_mov_b32 m0, s39
	s_nop 0
	buffer_load_dwordx4 v134, s[4:7], s16 offen lds
	s_mov_b32 m0, s40
	s_nop 0
	buffer_load_dwordx4 v134, s[8:11], s0 offen lds
	s_mov_b32 m0, s41
	s_nop 0
	buffer_load_dwordx4 v134, s[8:11], s17 offen lds
	s_mov_b32 m0, s42
	s_nop 0
	buffer_load_dwordx4 v134, s[4:7], s0 offen lds
	s_mov_b32 m0, s43
	s_nop 0
	buffer_load_dwordx4 v134, s[4:7], s17 offen lds
	s_and_saveexec_b64 s[6:7], vcc
	s_cbranch_execz .Lpf5_b0
	s_barrier
.Lpf5_b0:
	s_or_b64 exec, exec, s[6:7]
	s_mov_b32 s6, s10
	s_mov_b32 s7, s11
	s_waitcnt vmcnt(4)
	s_barrier
	s_mov_b32 m0, s45
	s_nop 0
	buffer_load_dwordx4 v134, s[8:11], s18 offen lds
	s_mov_b32 m0, s46
	s_nop 0
	buffer_load_dwordx4 v134, s[8:11], s19 offen lds
	s_mov_b32 m0, s47
	s_nop 0
	buffer_load_dwordx4 v134, s[4:7], s18 offen lds
	s_mov_b32 m0, s78
	s_nop 0
	buffer_load_dwordx4 v134, s[4:7], s19 offen lds
	s_mov_b32 m0, s82
	s_nop 0
	buffer_load_dwordx4 v134, s[8:11], s24 offen lds
	s_mov_b32 m0, s83
	s_nop 0
	buffer_load_dwordx4 v134, s[8:11], s25 offen lds
	s_waitcnt vmcnt(6)
	s_branch .Lpf5_join
.Lpf5_hdr:
	s_and_saveexec_b64 s[6:7], vcc
	s_cbranch_execz .Lpf5_b1
	s_barrier
.Lpf5_b1:
	s_or_b64 exec, exec, s[6:7]
	s_mov_b32 s6, s10
	s_mov_b32 s7, s11
	s_barrier
.Lpf5_join:
	v_and_b32_e32 v2, 15, v128
	v_lshlrev_b32_e32 v0, 12, v0
	v_and_b32_e32 v4, 0x3000, v0
	v_lshlrev_b32_e32 v0, 6, v2
	v_lshlrev_b32_e32 v2, 2, v128
	v_and_b32_e32 v3, 48, v128
	v_and_b32_e32 v2, 32, v2
	v_bitop3_b32 v0, v0, v2, v3 bitop3:0x36
	v_add_u32_e32 v5, s69, v0
	v_add_u32_e32 v6, s70, v0
	v_add_u32_e32 v7, s97, v0
	v_add_u32_e32 v8, s68, v0
	v_add_u32_e32 v9, 0, v0
	v_lshlrev_b32_e32 v0, 6, v128
	v_lshlrev_b32_e32 v1, 13, v1
	v_and_or_b32 v0, v0, s26, v3
	v_xad_u32 v2, v0, v2, 0
	v_or_b32_e32 v3, 0x800, v1
	v_or_b32_e32 v10, 0x1000, v1
	v_or_b32_e32 v11, 0x1800, v1
	v_mov_b32_e32 v0, 0
	s_add_i32 s79, s36, 0xc000
	s_add_i32 s67, s36, 0xe000
	s_mov_b32 s84, -2
	s_mov_b32 s85, 0x108180
	v_add_u32_e32 v137, v5, v4
	v_add_u32_e32 v132, v9, v1
	v_add_u32_e32 v131, v2, v3
	v_add_u32_e32 v130, v2, v10
	v_add_u32_e32 v129, v2, v11
	v_add_u32_e32 v136, v6, v4
	v_add_u32_e32 v135, v7, v4
	v_add_u32_e32 v133, v8, v4
	v_mov_b32_e32 v1, v0
	v_mov_b32_e32 v2, v0
	v_mov_b32_e32 v3, v0
	v_mov_b32_e32 v4, v0
	v_mov_b32_e32 v5, v0
	v_mov_b32_e32 v6, v0
	v_mov_b32_e32 v7, v0
	v_mov_b32_e32 v8, v0
	v_mov_b32_e32 v9, v0
	v_mov_b32_e32 v10, v0
	v_mov_b32_e32 v11, v0
	v_mov_b32_e32 v12, v0
	v_mov_b32_e32 v13, v0
	v_mov_b32_e32 v14, v0
	v_mov_b32_e32 v15, v0
	v_mov_b32_e32 v16, v0
	v_mov_b32_e32 v17, v0
	v_mov_b32_e32 v18, v0
	v_mov_b32_e32 v19, v0
	v_mov_b32_e32 v20, v0
	v_mov_b32_e32 v21, v0
	v_mov_b32_e32 v22, v0
	v_mov_b32_e32 v23, v0
	v_mov_b32_e32 v24, v0
	v_mov_b32_e32 v25, v0
	v_mov_b32_e32 v26, v0
	v_mov_b32_e32 v27, v0
	v_mov_b32_e32 v28, v0
	v_mov_b32_e32 v29, v0
	v_mov_b32_e32 v30, v0
	v_mov_b32_e32 v31, v0
	v_mov_b32_e32 v32, v0
	v_mov_b32_e32 v33, v0
	v_mov_b32_e32 v34, v0
	v_mov_b32_e32 v35, v0
	v_mov_b32_e32 v36, v0
	v_mov_b32_e32 v37, v0
	v_mov_b32_e32 v38, v0
	v_mov_b32_e32 v39, v0
	v_mov_b32_e32 v40, v0
	v_mov_b32_e32 v41, v0
	v_mov_b32_e32 v42, v0
	v_mov_b32_e32 v43, v0
	v_mov_b32_e32 v44, v0
	v_mov_b32_e32 v45, v0
	v_mov_b32_e32 v46, v0
	v_mov_b32_e32 v47, v0
	v_mov_b32_e32 v48, v0
	v_mov_b32_e32 v49, v0
	v_mov_b32_e32 v50, v0
	v_mov_b32_e32 v51, v0
	v_mov_b32_e32 v52, v0
	v_mov_b32_e32 v53, v0
	v_mov_b32_e32 v54, v0
	v_mov_b32_e32 v55, v0
	v_mov_b32_e32 v56, v0
	v_mov_b32_e32 v57, v0
	v_mov_b32_e32 v58, v0
	v_mov_b32_e32 v59, v0
	v_mov_b32_e32 v60, v0
	v_mov_b32_e32 v61, v0
	v_mov_b32_e32 v62, v0
	v_mov_b32_e32 v63, v0
	v_mov_b32_e32 v64, v0
	v_mov_b32_e32 v65, v0
	v_mov_b32_e32 v66, v0
; template <bool PEEL = false>
; __device__ __forceinline__ void gemm_tile(f32x4 (&acc)[2][2][4][2], const u16* __restrict__ A, int lda,
;                                           const u16* __restrict__ B, int K) {
;     ...
; #pragma unroll
;   for (int a = 0; a < 2; ++a)
; #pragma unroll
;     for (int b = 0; b < 2; ++b)
; #pragma unroll
;       for (int m = 0; m < 4; ++m)
; #pragma unroll
;         for (int n = 0; n < 2; ++n) acc[a][b][m][n] = f32x4{0.f, 0.f, 0.f, 0.f};
	v_mov_b32_e32 v67, v0
	v_mov_b32_e32 v68, v0
	v_mov_b32_e32 v69, v0
	v_mov_b32_e32 v70, v0
	v_mov_b32_e32 v71, v0
	v_mov_b32_e32 v72, v0
	v_mov_b32_e32 v73, v0
	v_mov_b32_e32 v74, v0
	v_mov_b32_e32 v75, v0
	v_mov_b32_e32 v76, v0
	v_mov_b32_e32 v77, v0
	v_mov_b32_e32 v78, v0
	v_mov_b32_e32 v79, v0
	v_mov_b32_e32 v80, v0
	v_mov_b32_e32 v81, v0
	v_mov_b32_e32 v82, v0
	v_mov_b32_e32 v83, v0
	v_mov_b32_e32 v84, v0
	v_mov_b32_e32 v85, v0
	v_mov_b32_e32 v86, v0
	v_mov_b32_e32 v87, v0
	v_mov_b32_e32 v88, v0
	v_mov_b32_e32 v89, v0
	v_mov_b32_e32 v90, v0
	v_mov_b32_e32 v91, v0
	v_mov_b32_e32 v92, v0
	v_mov_b32_e32 v93, v0
	v_mov_b32_e32 v94, v0
	v_mov_b32_e32 v95, v0
	v_mov_b32_e32 v96, v0
	v_mov_b32_e32 v97, v0
	v_mov_b32_e32 v98, v0
	v_mov_b32_e32 v99, v0
	v_mov_b32_e32 v100, v0
	v_mov_b32_e32 v101, v0
	v_mov_b32_e32 v102, v0
	v_mov_b32_e32 v103, v0
	v_mov_b32_e32 v104, v0
	v_mov_b32_e32 v105, v0
	v_mov_b32_e32 v106, v0
	v_mov_b32_e32 v107, v0
	v_mov_b32_e32 v108, v0
	v_mov_b32_e32 v109, v0
	v_mov_b32_e32 v110, v0
	v_mov_b32_e32 v111, v0
	v_mov_b32_e32 v112, v0
	v_mov_b32_e32 v113, v0
	v_mov_b32_e32 v114, v0
	v_mov_b32_e32 v115, v0
	v_mov_b32_e32 v116, v0
	v_mov_b32_e32 v117, v0
	v_mov_b32_e32 v118, v0
	v_mov_b32_e32 v119, v0
	v_mov_b32_e32 v120, v0
	v_mov_b32_e32 v121, v0
	v_mov_b32_e32 v122, v0
	v_mov_b32_e32 v123, v0
	v_mov_b32_e32 v124, v0
	v_mov_b32_e32 v125, v0
	v_mov_b32_e32 v126, v0
	v_mov_b32_e32 v127, v0
	s_barrier
.LBB0_153:
	ds_read_b128 v[138:141], v137
	ds_read_b128 v[142:145], v137 offset:1024
	ds_read_b128 v[146:149], v137 offset:2048
	ds_read_b128 v[150:153], v137 offset:3072
	s_mov_b32 m0, s79
	s_add_i32 s86, s85, 0xfffa7f00
	ds_read_b128 v[154:157], v132
	ds_read_b128 v[158:161], v132 offset:1024
	ds_read_b128 v[162:165], v131
	ds_read_b128 v[174:177], v131 offset:1024
	ds_read_b128 v[178:181], v130
	ds_read_b128 v[182:185], v130 offset:1024
	ds_read_b128 v[186:189], v129
	ds_read_b128 v[190:193], v129 offset:1024
	buffer_load_dwordx4 v134, s[4:7], s86 offen lds
	s_add_i32 s86, s85, 0xffffff00
	s_mov_b32 m0, s67
	s_nop 0
	buffer_load_dwordx4 v134, s[4:7], s86 offen lds
	s_waitcnt lgkmcnt(8)
	s_barrier
	s_waitcnt lgkmcnt(0)
	s_setprio 1
	s_waitcnt lgkmcnt(7)
	v_mfma_f32_16x16x32_bf16 v[124:127], v[154:157], v[138:141], v[124:127]
	v_mfma_f32_16x16x32_bf16 v[120:123], v[154:157], v[146:149], v[120:123]
	s_waitcnt lgkmcnt(5)
	v_mfma_f32_16x16x32_bf16 v[116:119], v[162:165], v[138:141], v[116:119]
	v_mfma_f32_16x16x32_bf16 v[112:115], v[162:165], v[146:149], v[112:115]
	s_waitcnt lgkmcnt(3)
	v_mfma_f32_16x16x32_bf16 v[108:111], v[178:181], v[138:141], v[108:111]
	v_mfma_f32_16x16x32_bf16 v[104:107], v[178:181], v[146:149], v[104:107]
	s_waitcnt lgkmcnt(1)
	v_mfma_f32_16x16x32_bf16 v[100:103], v[186:189], v[138:141], v[100:103]
	v_mfma_f32_16x16x32_bf16 v[96:99], v[186:189], v[146:149], v[96:99]
	v_mfma_f32_16x16x32_bf16 v[124:127], v[158:161], v[142:145], v[124:127]
	v_mfma_f32_16x16x32_bf16 v[120:123], v[158:161], v[150:153], v[120:123]
	v_mfma_f32_16x16x32_bf16 v[116:119], v[174:177], v[142:145], v[116:119]
	v_mfma_f32_16x16x32_bf16 v[112:115], v[174:177], v[150:153], v[112:115]
	v_mfma_f32_16x16x32_bf16 v[108:111], v[182:185], v[142:145], v[108:111]
	v_mfma_f32_16x16x32_bf16 v[104:107], v[182:185], v[150:153], v[104:107]
	s_waitcnt lgkmcnt(0)
	v_mfma_f32_16x16x32_bf16 v[100:103], v[190:193], v[142:145], v[100:103]
	v_mfma_f32_16x16x32_bf16 v[96:99], v[190:193], v[150:153], v[96:99]
	s_setprio 0
	s_barrier
	s_mov_b32 m0, s37
	s_add_i32 s86, s85, 0xffef7f80
	ds_read_b128 v[194:197], v136
	ds_read_b128 v[198:201], v136 offset:1024
	ds_read_b128 v[202:205], v136 offset:2048
	ds_read_b128 v[206:209], v136 offset:3072
	buffer_load_dwordx4 v134, s[8:11], s86 offen lds
	s_add_i32 s87, s85, 0xfff4ff80
	s_mov_b32 m0, s38
	s_nop 0
	buffer_load_dwordx4 v134, s[8:11], s87 offen lds
	s_barrier
	s_waitcnt lgkmcnt(0)
	s_setprio 1
	s_waitcnt lgkmcnt(3)
	v_mfma_f32_16x16x32_bf16 v[92:95], v[154:157], v[194:197], v[92:95]
	s_waitcnt lgkmcnt(1)
	v_mfma_f32_16x16x32_bf16 v[88:91], v[154:157], v[202:205], v[88:91]
	v_mfma_f32_16x16x32_bf16 v[84:87], v[162:165], v[194:197], v[84:87]
	v_mfma_f32_16x16x32_bf16 v[80:83], v[162:165], v[202:205], v[80:83]
	v_mfma_f32_16x16x32_bf16 v[76:79], v[178:181], v[194:197], v[76:79]
	v_mfma_f32_16x16x32_bf16 v[72:75], v[178:181], v[202:205], v[72:75]
	v_mfma_f32_16x16x32_bf16 v[68:71], v[186:189], v[194:197], v[68:71]
	v_mfma_f32_16x16x32_bf16 v[64:67], v[186:189], v[202:205], v[64:67]
	v_mfma_f32_16x16x32_bf16 v[92:95], v[158:161], v[198:201], v[92:95]
	s_waitcnt lgkmcnt(0)
	v_mfma_f32_16x16x32_bf16 v[88:91], v[158:161], v[206:209], v[88:91]
	v_mfma_f32_16x16x32_bf16 v[84:87], v[174:177], v[198:201], v[84:87]
	v_mfma_f32_16x16x32_bf16 v[80:83], v[174:177], v[206:209], v[80:83]
	v_mfma_f32_16x16x32_bf16 v[76:79], v[182:185], v[198:201], v[76:79]
	v_mfma_f32_16x16x32_bf16 v[72:75], v[182:185], v[206:209], v[72:75]
	v_mfma_f32_16x16x32_bf16 v[68:71], v[190:193], v[198:201], v[68:71]
	v_mfma_f32_16x16x32_bf16 v[64:67], v[190:193], v[206:209], v[64:67]
	s_setprio 0
	s_mov_b32 m0, s36
	s_barrier
	ds_read_b128 v[154:157], v132 offset:16384
	ds_read_b128 v[158:161], v132 offset:17408
	ds_read_b128 v[162:165], v131 offset:16384
	ds_read_b128 v[174:177], v131 offset:17408
	ds_read_b128 v[178:181], v130 offset:16384
	ds_read_b128 v[182:185], v130 offset:17408
	ds_read_b128 v[186:189], v129 offset:16384
	ds_read_b128 v[190:193], v129 offset:17408
	buffer_load_dwordx4 v134, s[4:7], s86 offen lds
	s_mov_b32 m0, s39
	s_nop 0
	buffer_load_dwordx4 v134, s[4:7], s87 offen lds
	s_barrier
	s_waitcnt lgkmcnt(0)
	s_setprio 1
	s_waitcnt lgkmcnt(7)
	v_mfma_f32_16x16x32_bf16 v[60:63], v[154:157], v[138:141], v[60:63]
	v_mfma_f32_16x16x32_bf16 v[56:59], v[154:157], v[146:149], v[56:59]
	s_waitcnt lgkmcnt(5)
	v_mfma_f32_16x16x32_bf16 v[52:55], v[162:165], v[138:141], v[52:55]
	v_mfma_f32_16x16x32_bf16 v[48:51], v[162:165], v[146:149], v[48:51]
	s_waitcnt lgkmcnt(3)
	v_mfma_f32_16x16x32_bf16 v[44:47], v[178:181], v[138:141], v[44:47]
	v_mfma_f32_16x16x32_bf16 v[40:43], v[178:181], v[146:149], v[40:43]
	s_waitcnt lgkmcnt(1)
	v_mfma_f32_16x16x32_bf16 v[36:39], v[186:189], v[138:141], v[36:39]
	v_mfma_f32_16x16x32_bf16 v[32:35], v[186:189], v[146:149], v[32:35]
	v_mfma_f32_16x16x32_bf16 v[60:63], v[158:161], v[142:145], v[60:63]
	v_mfma_f32_16x16x32_bf16 v[56:59], v[158:161], v[150:153], v[56:59]
	v_mfma_f32_16x16x32_bf16 v[52:55], v[174:177], v[142:145], v[52:55]
	v_mfma_f32_16x16x32_bf16 v[48:51], v[174:177], v[150:153], v[48:51]
	v_mfma_f32_16x16x32_bf16 v[44:47], v[182:185], v[142:145], v[44:47]
	v_mfma_f32_16x16x32_bf16 v[40:43], v[182:185], v[150:153], v[40:43]
	s_waitcnt lgkmcnt(0)
	v_mfma_f32_16x16x32_bf16 v[36:39], v[190:193], v[142:145], v[36:39]
	v_mfma_f32_16x16x32_bf16 v[32:35], v[190:193], v[150:153], v[32:35]
	s_setprio 0
	s_barrier
	s_mov_b32 m0, s40
	s_add_i32 s86, s85, 0xfffa7f80
	buffer_load_dwordx4 v134, s[8:11], s86 offen lds
	s_add_i32 s87, s85, 0xffffff80
	s_mov_b32 m0, s41
	s_nop 0
	buffer_load_dwordx4 v134, s[8:11], s87 offen lds
	s_waitcnt vmcnt(6)
	s_barrier
	s_setprio 1
	v_mfma_f32_16x16x32_bf16 v[28:31], v[154:157], v[194:197], v[28:31]
	v_mfma_f32_16x16x32_bf16 v[24:27], v[154:157], v[202:205], v[24:27]
	v_mfma_f32_16x16x32_bf16 v[20:23], v[162:165], v[194:197], v[20:23]
	v_mfma_f32_16x16x32_bf16 v[16:19], v[162:165], v[202:205], v[16:19]
	v_mfma_f32_16x16x32_bf16 v[12:15], v[178:181], v[194:197], v[12:15]
	v_mfma_f32_16x16x32_bf16 v[8:11], v[178:181], v[202:205], v[8:11]
	v_mfma_f32_16x16x32_bf16 v[4:7], v[186:189], v[194:197], v[4:7]
	v_mfma_f32_16x16x32_bf16 v[0:3], v[186:189], v[202:205], v[0:3]
	v_mfma_f32_16x16x32_bf16 v[28:31], v[158:161], v[198:201], v[28:31]
	v_mfma_f32_16x16x32_bf16 v[24:27], v[158:161], v[206:209], v[24:27]
	v_mfma_f32_16x16x32_bf16 v[20:23], v[174:177], v[198:201], v[20:23]
	v_mfma_f32_16x16x32_bf16 v[16:19], v[174:177], v[206:209], v[16:19]
	v_mfma_f32_16x16x32_bf16 v[12:15], v[182:185], v[198:201], v[12:15]
	v_mfma_f32_16x16x32_bf16 v[8:11], v[182:185], v[206:209], v[8:11]
	v_mfma_f32_16x16x32_bf16 v[4:7], v[190:193], v[198:201], v[4:7]
	v_mfma_f32_16x16x32_bf16 v[0:3], v[190:193], v[206:209], v[0:3]
	s_setprio 0
	s_barrier
	ds_read_b128 v[138:141], v135
	ds_read_b128 v[142:145], v135 offset:1024
	ds_read_b128 v[146:149], v135 offset:2048
	ds_read_b128 v[150:153], v135 offset:3072
	s_mov_b32 m0, s42
	ds_read_b128 v[154:157], v132 offset:32768
	ds_read_b128 v[158:161], v132 offset:33792
	ds_read_b128 v[162:165], v131 offset:32768
	ds_read_b128 v[174:177], v131 offset:33792
	ds_read_b128 v[178:181], v130 offset:32768
	ds_read_b128 v[182:185], v130 offset:33792
	ds_read_b128 v[186:189], v129 offset:32768
	ds_read_b128 v[190:193], v129 offset:33792
	buffer_load_dwordx4 v134, s[4:7], s86 offen lds
	s_mov_b32 m0, s43
	s_nop 0
	buffer_load_dwordx4 v134, s[4:7], s87 offen lds
	s_waitcnt lgkmcnt(8)
	s_barrier
	s_waitcnt lgkmcnt(0)
	s_setprio 1
	s_waitcnt lgkmcnt(7)
	v_mfma_f32_16x16x32_bf16 v[124:127], v[154:157], v[138:141], v[124:127]
	v_mfma_f32_16x16x32_bf16 v[120:123], v[154:157], v[146:149], v[120:123]
	s_waitcnt lgkmcnt(5)
	v_mfma_f32_16x16x32_bf16 v[116:119], v[162:165], v[138:141], v[116:119]
	v_mfma_f32_16x16x32_bf16 v[112:115], v[162:165], v[146:149], v[112:115]
	s_waitcnt lgkmcnt(3)
	v_mfma_f32_16x16x32_bf16 v[108:111], v[178:181], v[138:141], v[108:111]
	v_mfma_f32_16x16x32_bf16 v[104:107], v[178:181], v[146:149], v[104:107]
	s_waitcnt lgkmcnt(1)
	v_mfma_f32_16x16x32_bf16 v[100:103], v[186:189], v[138:141], v[100:103]
	v_mfma_f32_16x16x32_bf16 v[96:99], v[186:189], v[146:149], v[96:99]
	v_mfma_f32_16x16x32_bf16 v[124:127], v[158:161], v[142:145], v[124:127]
	v_mfma_f32_16x16x32_bf16 v[120:123], v[158:161], v[150:153], v[120:123]
	v_mfma_f32_16x16x32_bf16 v[116:119], v[174:177], v[142:145], v[116:119]
	v_mfma_f32_16x16x32_bf16 v[112:115], v[174:177], v[150:153], v[112:115]
	v_mfma_f32_16x16x32_bf16 v[108:111], v[182:185], v[142:145], v[108:111]
	v_mfma_f32_16x16x32_bf16 v[104:107], v[182:185], v[150:153], v[104:107]
	s_waitcnt lgkmcnt(0)
	v_mfma_f32_16x16x32_bf16 v[100:103], v[190:193], v[142:145], v[100:103]
	v_mfma_f32_16x16x32_bf16 v[96:99], v[190:193], v[150:153], v[96:99]
	s_setprio 0
	s_barrier
	s_mov_b32 m0, s45
	s_add_i32 s86, s85, 0xffef8000
	ds_read_b128 v[194:197], v133
	ds_read_b128 v[198:201], v133 offset:1024
	ds_read_b128 v[202:205], v133 offset:2048
	ds_read_b128 v[206:209], v133 offset:3072
	buffer_load_dwordx4 v134, s[8:11], s86 offen lds
	s_add_i32 s87, s85, 0xfff50000
	s_mov_b32 m0, s46
	s_nop 0
	buffer_load_dwordx4 v134, s[8:11], s87 offen lds
	s_barrier
; #define LDA(dst, b, h)                                                                             \
;   _Pragma("unroll") for (int m = 0; m < 4; ++m) _Pragma("unroll") for (int k = 0; k < 2; ++k)      \
;       dst[m][k] = *reinterpret_cast<const bf16x8*>(SA(b, h) + lds_byte(wr * 64 + m * 16 + fr, k * 32 + fq * 8))
; #define LDB(dst, b, h)                                                                             \
;   _Pragma("unroll") for (int n = 0; n < 2; ++n) _Pragma("unroll") for (int k = 0; k < 2; ++k)      \
;       dst[n][k] = *reinterpret_cast<const bf16x8*>(SB(b, h) + lds_byte(wc * 32 + n * 16 + fr, k * 32 + fq * 8))
; template <bool PEEL = false>
; __device__ __forceinline__ void gemm_tile(f32x4 (&acc)[2][2][4][2], const u16* __restrict__ A, int lda,
;                                           const u16* __restrict__ B, int K) {
;     ...
;     LDB(B0, 0, 0); LDA(At, 0, 0); STAGE_A(SA(1, 1), 1, nt - 1);
	s_waitcnt lgkmcnt(0)
	s_setprio 1
	s_waitcnt lgkmcnt(3)
	v_mfma_f32_16x16x32_bf16 v[92:95], v[154:157], v[194:197], v[92:95]
	s_waitcnt lgkmcnt(1)
	v_mfma_f32_16x16x32_bf16 v[88:91], v[154:157], v[202:205], v[88:91]
	v_mfma_f32_16x16x32_bf16 v[84:87], v[162:165], v[194:197], v[84:87]
	v_mfma_f32_16x16x32_bf16 v[80:83], v[162:165], v[202:205], v[80:83]
	v_mfma_f32_16x16x32_bf16 v[76:79], v[178:181], v[194:197], v[76:79]
	v_mfma_f32_16x16x32_bf16 v[72:75], v[178:181], v[202:205], v[72:75]
	v_mfma_f32_16x16x32_bf16 v[68:71], v[186:189], v[194:197], v[68:71]
	v_mfma_f32_16x16x32_bf16 v[64:67], v[186:189], v[202:205], v[64:67]
	v_mfma_f32_16x16x32_bf16 v[92:95], v[158:161], v[198:201], v[92:95]
	s_waitcnt lgkmcnt(0)
	v_mfma_f32_16x16x32_bf16 v[88:91], v[158:161], v[206:209], v[88:91]
	v_mfma_f32_16x16x32_bf16 v[84:87], v[174:177], v[198:201], v[84:87]
	v_mfma_f32_16x16x32_bf16 v[80:83], v[174:177], v[206:209], v[80:83]
	v_mfma_f32_16x16x32_bf16 v[76:79], v[182:185], v[198:201], v[76:79]
	v_mfma_f32_16x16x32_bf16 v[72:75], v[182:185], v[206:209], v[72:75]
	v_mfma_f32_16x16x32_bf16 v[68:71], v[190:193], v[198:201], v[68:71]
	v_mfma_f32_16x16x32_bf16 v[64:67], v[190:193], v[206:209], v[64:67]
	s_setprio 0
	s_mov_b32 m0, s47
	s_barrier
	ds_read_b128 v[154:157], v132 offset:49152
	ds_read_b128 v[158:161], v132 offset:50176
	ds_read_b128 v[162:165], v131 offset:49152
	ds_read_b128 v[174:177], v131 offset:50176
	ds_read_b128 v[178:181], v130 offset:49152
	ds_read_b128 v[182:185], v130 offset:50176
	ds_read_b128 v[186:189], v129 offset:49152
	ds_read_b128 v[190:193], v129 offset:50176
	buffer_load_dwordx4 v134, s[4:7], s86 offen lds
	s_mov_b32 m0, s78
	s_nop 0
	buffer_load_dwordx4 v134, s[4:7], s87 offen lds
	s_barrier
	s_waitcnt lgkmcnt(0)
	s_setprio 1
	s_waitcnt lgkmcnt(7)
	v_mfma_f32_16x16x32_bf16 v[60:63], v[154:157], v[138:141], v[60:63]
	v_mfma_f32_16x16x32_bf16 v[56:59], v[154:157], v[146:149], v[56:59]
	s_waitcnt lgkmcnt(5)
	v_mfma_f32_16x16x32_bf16 v[52:55], v[162:165], v[138:141], v[52:55]
	v_mfma_f32_16x16x32_bf16 v[48:51], v[162:165], v[146:149], v[48:51]
	s_waitcnt lgkmcnt(3)
	v_mfma_f32_16x16x32_bf16 v[44:47], v[178:181], v[138:141], v[44:47]
	v_mfma_f32_16x16x32_bf16 v[40:43], v[178:181], v[146:149], v[40:43]
	s_waitcnt lgkmcnt(1)
	v_mfma_f32_16x16x32_bf16 v[36:39], v[186:189], v[138:141], v[36:39]
	v_mfma_f32_16x16x32_bf16 v[32:35], v[186:189], v[146:149], v[32:35]
	v_mfma_f32_16x16x32_bf16 v[60:63], v[158:161], v[142:145], v[60:63]
	v_mfma_f32_16x16x32_bf16 v[56:59], v[158:161], v[150:153], v[56:59]
	v_mfma_f32_16x16x32_bf16 v[52:55], v[174:177], v[142:145], v[52:55]
	v_mfma_f32_16x16x32_bf16 v[48:51], v[174:177], v[150:153], v[48:51]
	v_mfma_f32_16x16x32_bf16 v[44:47], v[182:185], v[142:145], v[44:47]
	v_mfma_f32_16x16x32_bf16 v[40:43], v[182:185], v[150:153], v[40:43]
	s_waitcnt lgkmcnt(0)
	v_mfma_f32_16x16x32_bf16 v[36:39], v[190:193], v[142:145], v[36:39]
	v_mfma_f32_16x16x32_bf16 v[32:35], v[190:193], v[150:153], v[32:35]
	s_setprio 0
	s_barrier
	s_add_i32 s86, s85, 0xfffa8000
	s_mov_b32 m0, s82
	s_nop 0
	buffer_load_dwordx4 v134, s[8:11], s86 offen lds
	s_mov_b32 m0, s83
	s_nop 0
	buffer_load_dwordx4 v134, s[8:11], s85 offen lds
	s_waitcnt vmcnt(6)
	s_barrier
	s_setprio 1
	v_mfma_f32_16x16x32_bf16 v[28:31], v[154:157], v[194:197], v[28:31]
	v_mfma_f32_16x16x32_bf16 v[24:27], v[154:157], v[202:205], v[24:27]
	v_mfma_f32_16x16x32_bf16 v[20:23], v[162:165], v[194:197], v[20:23]
	v_mfma_f32_16x16x32_bf16 v[16:19], v[162:165], v[202:205], v[16:19]
	v_mfma_f32_16x16x32_bf16 v[12:15], v[178:181], v[194:197], v[12:15]
	v_mfma_f32_16x16x32_bf16 v[8:11], v[178:181], v[202:205], v[8:11]
	v_mfma_f32_16x16x32_bf16 v[4:7], v[186:189], v[194:197], v[4:7]
	v_mfma_f32_16x16x32_bf16 v[0:3], v[186:189], v[202:205], v[0:3]
	v_mfma_f32_16x16x32_bf16 v[28:31], v[158:161], v[198:201], v[28:31]
	v_mfma_f32_16x16x32_bf16 v[24:27], v[158:161], v[206:209], v[24:27]
	v_mfma_f32_16x16x32_bf16 v[20:23], v[174:177], v[198:201], v[20:23]
	v_mfma_f32_16x16x32_bf16 v[16:19], v[174:177], v[206:209], v[16:19]
	v_mfma_f32_16x16x32_bf16 v[12:15], v[182:185], v[198:201], v[12:15]
	v_mfma_f32_16x16x32_bf16 v[8:11], v[182:185], v[206:209], v[8:11]
	v_mfma_f32_16x16x32_bf16 v[4:7], v[190:193], v[198:201], v[4:7]
	v_mfma_f32_16x16x32_bf16 v[0:3], v[190:193], v[206:209], v[0:3]
	s_setprio 0
	s_add_i32 s84, s84, 2
	s_addk_i32 s85, 0x100
	s_cmp_lt_u32 s84, 40
	s_barrier
	s_cbranch_scc1 .LBB0_153
	v_mov_b32_e32 v250, v134
	s_mov_b32 s6, s10
	s_mov_b32 s7, s11
	s_mov_b32 m0, s79
	ds_read_b128 v[138:141], v137
	ds_read_b128 v[142:145], v137 offset:1024
	ds_read_b128 v[146:149], v137 offset:2048
	ds_read_b128 v[150:153], v137 offset:3072
	ds_read_b128 v[154:157], v132
	ds_read_b128 v[158:161], v132 offset:1024
	ds_read_b128 v[162:165], v131
	ds_read_b128 v[174:177], v131 offset:1024
	ds_read_b128 v[178:181], v130
	ds_read_b128 v[182:185], v130 offset:1024
	ds_read_b128 v[186:189], v129
	ds_read_b128 v[190:193], v129 offset:1024
	buffer_load_dwordx4 v134, s[4:7], s29 offen lds
	s_mov_b32 m0, s67
	s_nop 0
	buffer_load_dwordx4 v134, s[4:7], s30 offen lds
	s_barrier
; #define LDA(dst, b, h)                                                                             \
;   _Pragma("unroll") for (int m = 0; m < 4; ++m) _Pragma("unroll") for (int k = 0; k < 2; ++k)      \
;       dst[m][k] = *reinterpret_cast<const bf16x8*>(SA(b, h) + lds_byte(wr * 64 + m * 16 + fr, k * 32 + fq * 8))
; #define LDB(dst, b, h)                                                                             \
;   _Pragma("unroll") for (int n = 0; n < 2; ++n) _Pragma("unroll") for (int k = 0; k < 2; ++k)      \
;       dst[n][k] = *reinterpret_cast<const bf16x8*>(SB(b, h) + lds_byte(wc * 32 + n * 16 + fr, k * 32 + fq * 8))
; #define WAIT_V(n) asm volatile("s_waitcnt vmcnt(" #n ")" ::: "memory")
; #define WAIT_L(n) asm volatile("s_waitcnt lgkmcnt(" #n ")" ::: "memory")
; #define BAR __builtin_amdgcn_s_barrier()
; template <bool PEEL = false>
; __device__ __forceinline__ void gemm_tile(f32x4 (&acc)[2][2][4][2], const u16* __restrict__ A, int lda,
;                                           const u16* __restrict__ B, int K) {
;     ...
;     BAR; WAIT_L(0); MMA(0, 0, At, B0); BAR;
;     LDB(B1, 0, 1); BAR; WAIT_L(0); MMA(0, 1, At, B1); BAR;
;     LDA(At, 0, 1); WAIT_V(4); BAR; WAIT_L(0); MMA(1, 0, At, B0); MMA(1, 1, At, B1); BAR;
;   }
;   {
;     LDB(B0, 1, 0); LDA(At, 1, 0); WAIT_V(2); BAR; WAIT_L(0); MMA(0, 0, At, B0); BAR;
	s_waitcnt lgkmcnt(0)
	s_setprio 1
	s_waitcnt lgkmcnt(7)
	v_mfma_f32_16x16x32_bf16 v[124:127], v[154:157], v[138:141], v[124:127]
	v_mfma_f32_16x16x32_bf16 v[120:123], v[154:157], v[146:149], v[120:123]
	s_waitcnt lgkmcnt(3)
	v_mfma_f32_16x16x32_bf16 v[108:111], v[178:181], v[138:141], v[108:111]
	v_mfma_f32_16x16x32_bf16 v[104:107], v[178:181], v[146:149], v[104:107]
	v_mfma_f32_16x16x32_bf16 v[124:127], v[158:161], v[142:145], v[124:127]
	v_mfma_f32_16x16x32_bf16 v[120:123], v[158:161], v[150:153], v[120:123]
	v_mfma_f32_16x16x32_bf16 v[116:119], v[162:165], v[138:141], v[116:119]
	v_mfma_f32_16x16x32_bf16 v[112:115], v[162:165], v[146:149], v[112:115]
	s_waitcnt lgkmcnt(2)
	v_mfma_f32_16x16x32_bf16 v[108:111], v[182:185], v[142:145], v[108:111]
	v_mfma_f32_16x16x32_bf16 v[104:107], v[182:185], v[150:153], v[104:107]
	s_waitcnt lgkmcnt(1)
	v_mfma_f32_16x16x32_bf16 v[100:103], v[186:189], v[138:141], v[100:103]
	v_mfma_f32_16x16x32_bf16 v[96:99], v[186:189], v[146:149], v[96:99]
	v_mfma_f32_16x16x32_bf16 v[194:197], v[174:177], v[142:145], v[116:119]
	v_mfma_f32_16x16x32_bf16 v[198:201], v[174:177], v[150:153], v[112:115]
	s_waitcnt lgkmcnt(0)
	v_mfma_f32_16x16x32_bf16 v[202:205], v[190:193], v[142:145], v[100:103]
	v_mfma_f32_16x16x32_bf16 v[206:209], v[190:193], v[150:153], v[96:99]
	s_setprio 0
	s_barrier
	s_nop 0
	ds_read_b128 v[96:99], v136
	ds_read_b128 v[100:103], v136 offset:1024
	ds_read_b128 v[112:115], v136 offset:2048
	ds_read_b128 v[116:119], v136 offset:3072
	s_barrier
	s_waitcnt lgkmcnt(0)
	s_setprio 1
	s_waitcnt lgkmcnt(3)
	v_mfma_f32_16x16x32_bf16 v[92:95], v[154:157], v[96:99], v[92:95]
	s_waitcnt lgkmcnt(1)
	v_mfma_f32_16x16x32_bf16 v[88:91], v[154:157], v[112:115], v[88:91]
	v_mfma_f32_16x16x32_bf16 v[76:79], v[178:181], v[96:99], v[76:79]
	v_mfma_f32_16x16x32_bf16 v[72:75], v[178:181], v[112:115], v[72:75]
	v_mfma_f32_16x16x32_bf16 v[92:95], v[158:161], v[100:103], v[92:95]
	s_waitcnt lgkmcnt(0)
	v_mfma_f32_16x16x32_bf16 v[88:91], v[158:161], v[116:119], v[88:91]
	v_mfma_f32_16x16x32_bf16 v[84:87], v[162:165], v[96:99], v[84:87]
	v_mfma_f32_16x16x32_bf16 v[80:83], v[162:165], v[112:115], v[80:83]
	v_mfma_f32_16x16x32_bf16 v[76:79], v[182:185], v[100:103], v[76:79]
	v_mfma_f32_16x16x32_bf16 v[72:75], v[182:185], v[116:119], v[72:75]
	v_mfma_f32_16x16x32_bf16 v[68:71], v[186:189], v[96:99], v[68:71]
	v_mfma_f32_16x16x32_bf16 v[64:67], v[186:189], v[112:115], v[64:67]
	v_mfma_f32_16x16x32_bf16 v[154:157], v[174:177], v[100:103], v[84:87]
	v_mfma_f32_16x16x32_bf16 v[158:161], v[174:177], v[116:119], v[80:83]
	v_mfma_f32_16x16x32_bf16 v[162:165], v[190:193], v[100:103], v[68:71]
	v_mfma_f32_16x16x32_bf16 v[174:177], v[190:193], v[116:119], v[64:67]
	s_setprio 0
	s_barrier
	s_nop 1
	ds_read_b128 v[64:67], v132 offset:16384
	ds_read_b128 v[68:71], v132 offset:17408
	ds_read_b128 v[80:83], v131 offset:16384
	ds_read_b128 v[84:87], v131 offset:17408
	ds_read_b128 v[178:181], v130 offset:16384
	ds_read_b128 v[182:185], v130 offset:17408
	ds_read_b128 v[186:189], v129 offset:16384
	ds_read_b128 v[190:193], v129 offset:17408
	s_waitcnt vmcnt(4)
	s_barrier
	s_waitcnt lgkmcnt(0)
	s_setprio 1
	s_waitcnt lgkmcnt(7)
	v_mfma_f32_16x16x32_bf16 v[60:63], v[64:67], v[138:141], v[60:63]
	v_mfma_f32_16x16x32_bf16 v[56:59], v[64:67], v[146:149], v[56:59]
	s_waitcnt lgkmcnt(3)
	v_mfma_f32_16x16x32_bf16 v[44:47], v[178:181], v[138:141], v[44:47]
	v_mfma_f32_16x16x32_bf16 v[40:43], v[178:181], v[146:149], v[40:43]
	v_mfma_f32_16x16x32_bf16 v[60:63], v[68:71], v[142:145], v[60:63]
	v_mfma_f32_16x16x32_bf16 v[56:59], v[68:71], v[150:153], v[56:59]
	v_mfma_f32_16x16x32_bf16 v[52:55], v[80:83], v[138:141], v[52:55]
	v_mfma_f32_16x16x32_bf16 v[48:51], v[80:83], v[146:149], v[48:51]
	s_waitcnt lgkmcnt(2)
	v_mfma_f32_16x16x32_bf16 v[44:47], v[182:185], v[142:145], v[44:47]
	v_mfma_f32_16x16x32_bf16 v[40:43], v[182:185], v[150:153], v[40:43]
	s_waitcnt lgkmcnt(1)
	v_mfma_f32_16x16x32_bf16 v[36:39], v[186:189], v[138:141], v[36:39]
	v_mfma_f32_16x16x32_bf16 v[32:35], v[186:189], v[146:149], v[32:35]
	v_mfma_f32_16x16x32_bf16 v[210:213], v[84:87], v[142:145], v[52:55]
	v_mfma_f32_16x16x32_bf16 v[214:217], v[84:87], v[150:153], v[48:51]
	s_waitcnt lgkmcnt(0)
	v_mfma_f32_16x16x32_bf16 v[136:139], v[190:193], v[142:145], v[36:39]
	v_mfma_f32_16x16x32_bf16 v[140:143], v[190:193], v[150:153], v[32:35]
	s_setprio 0
	s_setprio 1
	v_mfma_f32_16x16x32_bf16 v[28:31], v[64:67], v[96:99], v[28:31]
	v_mfma_f32_16x16x32_bf16 v[24:27], v[64:67], v[112:115], v[24:27]
	v_mfma_f32_16x16x32_bf16 v[12:15], v[178:181], v[96:99], v[12:15]
	v_mfma_f32_16x16x32_bf16 v[8:11], v[178:181], v[112:115], v[8:11]
	v_mfma_f32_16x16x32_bf16 v[28:31], v[68:71], v[100:103], v[28:31]
	v_mfma_f32_16x16x32_bf16 v[24:27], v[68:71], v[116:119], v[24:27]
	v_mfma_f32_16x16x32_bf16 v[20:23], v[80:83], v[96:99], v[20:23]
	v_mfma_f32_16x16x32_bf16 v[16:19], v[80:83], v[112:115], v[16:19]
	v_mfma_f32_16x16x32_bf16 v[12:15], v[182:185], v[100:103], v[12:15]
	v_mfma_f32_16x16x32_bf16 v[8:11], v[182:185], v[116:119], v[8:11]
	v_mfma_f32_16x16x32_bf16 v[4:7], v[186:189], v[96:99], v[4:7]
	v_mfma_f32_16x16x32_bf16 v[0:3], v[186:189], v[112:115], v[0:3]
	v_mfma_f32_16x16x32_bf16 v[144:147], v[84:87], v[100:103], v[20:23]
	v_mfma_f32_16x16x32_bf16 v[148:151], v[84:87], v[116:119], v[16:19]
	v_mfma_f32_16x16x32_bf16 v[178:181], v[190:193], v[100:103], v[4:7]
	v_mfma_f32_16x16x32_bf16 v[182:185], v[190:193], v[116:119], v[0:3]
	s_setprio 0
	s_barrier
; #define LDA(dst, b, h)                                                                             \
;   _Pragma("unroll") for (int m = 0; m < 4; ++m) _Pragma("unroll") for (int k = 0; k < 2; ++k)      \
;       dst[m][k] = *reinterpret_cast<const bf16x8*>(SA(b, h) + lds_byte(wr * 64 + m * 16 + fr, k * 32 + fq * 8))
; #define LDB(dst, b, h)                                                                             \
;   _Pragma("unroll") for (int n = 0; n < 2; ++n) _Pragma("unroll") for (int k = 0; k < 2; ++k)      \
;       dst[n][k] = *reinterpret_cast<const bf16x8*>(SB(b, h) + lds_byte(wc * 32 + n * 16 + fr, k * 32 + fq * 8))
; #define WAIT_V(n) asm volatile("s_waitcnt vmcnt(" #n ")" ::: "memory")
; #define WAIT_L(n) asm volatile("s_waitcnt lgkmcnt(" #n ")" ::: "memory")
; #define BAR __builtin_amdgcn_s_barrier()
; template <bool PEEL = false>
; __device__ __forceinline__ void gemm_tile(f32x4 (&acc)[2][2][4][2], const u16* __restrict__ A, int lda,
;                                           const u16* __restrict__ B, int K) {
;     ...
;     LDB(B0, 1, 0); LDA(At, 1, 0); WAIT_V(2); BAR; WAIT_L(0); MMA(0, 0, At, B0); BAR;
;     LDB(B1, 1, 1); WAIT_V(0); BAR; WAIT_L(0); MMA(0, 1, At, B1); BAR;
;     LDA(At, 1, 1); BAR; WAIT_L(0); MMA(1, 0, At, B0); MMA(1, 1, At, B1); BAR;
;   }
;   if (wr == 0) BAR;
	s_nop 1
	ds_read_b128 v[0:3], v135
	ds_read_b128 v[4:7], v135 offset:1024
	ds_read_b128 v[186:189], v135 offset:2048
	ds_read_b128 v[190:193], v135 offset:3072
	ds_read_b128 v[16:19], v132 offset:32768
	ds_read_b128 v[20:23], v132 offset:33792
	ds_read_b128 v[32:35], v131 offset:32768
	ds_read_b128 v[36:39], v131 offset:33792
	ds_read_b128 v[48:51], v130 offset:32768
	ds_read_b128 v[52:55], v130 offset:33792
	ds_read_b128 v[218:221], v129 offset:32768
	ds_read_b128 v[222:225], v129 offset:33792
	s_waitcnt vmcnt(2)
	s_barrier
	s_waitcnt lgkmcnt(0)
	s_setprio 1
	s_waitcnt lgkmcnt(7)
	v_mfma_f32_16x16x32_bf16 v[64:67], v[16:19], v[0:3], v[124:127]
	s_waitcnt lgkmcnt(6)
	v_mfma_f32_16x16x32_bf16 v[112:115], v[20:23], v[4:7], v[64:67]
	v_mfma_f32_16x16x32_bf16 v[64:67], v[16:19], v[186:189], v[120:123]
	v_mfma_f32_16x16x32_bf16 v[116:119], v[20:23], v[190:193], v[64:67]
	s_waitcnt lgkmcnt(5)
	v_mfma_f32_16x16x32_bf16 v[64:67], v[32:35], v[0:3], v[194:197]
	s_waitcnt lgkmcnt(4)
	v_mfma_f32_16x16x32_bf16 v[96:99], v[36:39], v[4:7], v[64:67]
	v_mfma_f32_16x16x32_bf16 v[64:67], v[32:35], v[186:189], v[198:201]
	v_mfma_f32_16x16x32_bf16 v[100:103], v[36:39], v[190:193], v[64:67]
	s_waitcnt lgkmcnt(3)
	v_mfma_f32_16x16x32_bf16 v[64:67], v[48:51], v[0:3], v[108:111]
	s_waitcnt lgkmcnt(2)
	v_mfma_f32_16x16x32_bf16 v[80:83], v[52:55], v[4:7], v[64:67]
	v_mfma_f32_16x16x32_bf16 v[64:67], v[48:51], v[186:189], v[104:107]
	v_mfma_f32_16x16x32_bf16 v[84:87], v[52:55], v[190:193], v[64:67]
	s_waitcnt lgkmcnt(1)
	v_mfma_f32_16x16x32_bf16 v[64:67], v[218:221], v[0:3], v[202:205]
	v_mfma_f32_16x16x32_bf16 v[68:71], v[218:221], v[186:189], v[206:209]
	s_waitcnt lgkmcnt(0)
	v_mfma_f32_16x16x32_bf16 v[64:67], v[222:225], v[4:7], v[64:67]
	v_mfma_f32_16x16x32_bf16 v[68:71], v[222:225], v[190:193], v[68:71]
	s_setprio 0
	s_barrier
	ds_read_b128 v[194:197], v133
	ds_read_b128 v[198:201], v133 offset:1024
	ds_read_b128 v[202:205], v133 offset:2048
	ds_read_b128 v[206:209], v133 offset:3072
	s_waitcnt vmcnt(0)
	s_barrier
	s_waitcnt lgkmcnt(0)
	s_setprio 1
	s_waitcnt lgkmcnt(3)
	v_mfma_f32_16x16x32_bf16 v[92:95], v[16:19], v[194:197], v[92:95]
	s_waitcnt lgkmcnt(1)
	v_mfma_f32_16x16x32_bf16 v[16:19], v[16:19], v[202:205], v[88:91]
	s_waitcnt lgkmcnt(0)
	v_mfma_f32_16x16x32_bf16 v[124:127], v[20:23], v[206:209], v[16:19]
	v_mfma_f32_16x16x32_bf16 v[16:19], v[32:35], v[194:197], v[154:157]
	v_mfma_f32_16x16x32_bf16 v[104:107], v[36:39], v[198:201], v[16:19]
	v_mfma_f32_16x16x32_bf16 v[16:19], v[32:35], v[202:205], v[158:161]
	v_mfma_f32_16x16x32_bf16 v[108:111], v[36:39], v[206:209], v[16:19]
	v_mfma_f32_16x16x32_bf16 v[16:19], v[48:51], v[194:197], v[76:79]
	v_mfma_f32_16x16x32_bf16 v[88:91], v[52:55], v[198:201], v[16:19]
	v_mfma_f32_16x16x32_bf16 v[16:19], v[48:51], v[202:205], v[72:75]
	v_mfma_f32_16x16x32_bf16 v[120:123], v[20:23], v[198:201], v[92:95]
	v_mfma_f32_16x16x32_bf16 v[92:95], v[52:55], v[206:209], v[16:19]
	v_mfma_f32_16x16x32_bf16 v[16:19], v[218:221], v[194:197], v[162:165]
	v_mfma_f32_16x16x32_bf16 v[72:75], v[222:225], v[198:201], v[16:19]
	v_mfma_f32_16x16x32_bf16 v[16:19], v[218:221], v[202:205], v[174:177]
	v_mfma_f32_16x16x32_bf16 v[76:79], v[222:225], v[206:209], v[16:19]
	s_setprio 0
	s_barrier
	ds_read_b128 v[152:155], v132 offset:49152
	ds_read_b128 v[132:135], v132 offset:50176
	ds_read_b128 v[156:159], v131 offset:49152
	ds_read_b128 v[160:163], v131 offset:50176
	ds_read_b128 v[164:167], v130 offset:49152
	ds_read_b128 v[174:177], v130 offset:50176
	ds_read_b128 v[218:221], v129 offset:49152
	ds_read_b128 v[222:225], v129 offset:50176
	s_barrier
	s_waitcnt lgkmcnt(0)
	s_setprio 1
	s_waitcnt lgkmcnt(7)
	v_mfma_f32_16x16x32_bf16 v[16:19], v[152:155], v[0:3], v[60:63]
	s_waitcnt lgkmcnt(6)
	v_mfma_f32_16x16x32_bf16 v[48:51], v[132:135], v[4:7], v[16:19]
	v_mfma_f32_16x16x32_bf16 v[16:19], v[152:155], v[186:189], v[56:59]
	v_mfma_f32_16x16x32_bf16 v[52:55], v[132:135], v[190:193], v[16:19]
	s_waitcnt lgkmcnt(5)
	v_mfma_f32_16x16x32_bf16 v[16:19], v[156:159], v[0:3], v[210:213]
	s_waitcnt lgkmcnt(4)
	v_mfma_f32_16x16x32_bf16 v[32:35], v[160:163], v[4:7], v[16:19]
	v_mfma_f32_16x16x32_bf16 v[16:19], v[156:159], v[186:189], v[214:217]
	v_mfma_f32_16x16x32_bf16 v[36:39], v[160:163], v[190:193], v[16:19]
	s_waitcnt lgkmcnt(3)
	v_mfma_f32_16x16x32_bf16 v[16:19], v[164:167], v[0:3], v[44:47]
	s_waitcnt lgkmcnt(1)
	v_mfma_f32_16x16x32_bf16 v[0:3], v[218:221], v[0:3], v[136:139]
	v_mfma_f32_16x16x32_bf16 v[16:19], v[174:177], v[4:7], v[16:19]
	v_mfma_f32_16x16x32_bf16 v[20:23], v[164:167], v[186:189], v[40:43]
	s_waitcnt lgkmcnt(0)
	v_mfma_f32_16x16x32_bf16 v[0:3], v[222:225], v[4:7], v[0:3]
	v_mfma_f32_16x16x32_bf16 v[4:7], v[218:221], v[186:189], v[140:143]
	v_mfma_f32_16x16x32_bf16 v[20:23], v[174:177], v[190:193], v[20:23]
	v_mfma_f32_16x16x32_bf16 v[4:7], v[222:225], v[190:193], v[4:7]
	s_setprio 0
	s_setprio 1
	v_mfma_f32_16x16x32_bf16 v[24:27], v[152:155], v[202:205], v[24:27]
	v_mfma_f32_16x16x32_bf16 v[60:63], v[132:135], v[206:209], v[24:27]
	v_mfma_f32_16x16x32_bf16 v[24:27], v[156:159], v[194:197], v[144:147]
	v_mfma_f32_16x16x32_bf16 v[28:31], v[152:155], v[194:197], v[28:31]
	v_mfma_f32_16x16x32_bf16 v[40:43], v[160:163], v[198:201], v[24:27]
	v_mfma_f32_16x16x32_bf16 v[24:27], v[156:159], v[202:205], v[148:151]
	v_mfma_f32_16x16x32_bf16 v[12:15], v[164:167], v[194:197], v[12:15]
	v_mfma_f32_16x16x32_bf16 v[8:11], v[164:167], v[202:205], v[8:11]
	v_mfma_f32_16x16x32_bf16 v[56:59], v[132:135], v[198:201], v[28:31]
	v_mfma_f32_16x16x32_bf16 v[44:47], v[160:163], v[206:209], v[24:27]
	v_mfma_f32_16x16x32_bf16 v[24:27], v[174:177], v[198:201], v[12:15]
	v_mfma_f32_16x16x32_bf16 v[28:31], v[174:177], v[206:209], v[8:11]
	v_mfma_f32_16x16x32_bf16 v[8:11], v[218:221], v[194:197], v[178:181]
	v_mfma_f32_16x16x32_bf16 v[12:15], v[218:221], v[202:205], v[182:185]
	v_mfma_f32_16x16x32_bf16 v[8:11], v[222:225], v[198:201], v[8:11]
	v_mfma_f32_16x16x32_bf16 v[12:15], v[222:225], v[206:209], v[12:15]
	s_setprio 0
	v_cmp_gt_u32_e32 vcc, s28, v128
	s_barrier
	s_and_saveexec_b64 s[4:5], vcc
	s_cbranch_execz .LBB0_156
	s_barrier
; #define EPI_VARS                                                                                  \
;   int wr = wr0, wc = wc0, fr = fr0, fq = fq0;                                                     \
;   asm volatile("" : "+v"(wr), "+v"(wc), "+v"(fr), "+v"(fq));
; template <bool WRITE_B, bool FINAL>
; __device__ __forceinline__ void gemm_resid_xcd(const P& p, const u16* __restrict__ Wt, float scale) {
;     ...
;   for (int i = 0; i < 4; ++i) {
;     const int mt = i * 64 + (b & 7) + 8 * (b >> 5);
;     const u16* A = (const u16*)(p.ws + OFF_BIG) + (size_t)mt * BIG_BLK;
;     const size_t row0 = (size_t)mt * 256;
;     f32x4 acc[2][2][4][2];
;     gemm_tile(acc, A, DFF, Wt + (size_t)n * 256 * DFF, DFF);
;     {
;       EPI_VARS
; #pragma unroll
;       for (int ai = 0; ai < 2; ++ai) {
;       uint2 rv[1][4][4];
; #pragma unroll
;         for (int m = 0; m < 4; ++m)
; #pragma unroll
;           for (int j = 0; j < 4; ++j)
;             rv[0][m][j] = *(const uint2*)((const u16*)(p.ws + OFF_ACTB) + (row0 + ai * 128 + wr * 64 + m * 16 + fq * 4 + j) * 1024 + n * 256 + wc * 64 + fr * 4);
; #pragma unroll
;         for (int m = 0; m < 4; ++m)
; #pragma unroll
;           for (int j = 0; j < 4; ++j) {
;             const int row = ai * 128 + wr * 64 + m * 16 + fq * 4 + j;
;             const size_t idx = (row0 + row) * 1024 + n * 256 + wc * 64 + fr * 4;
;             u16* rp = (u16*)(p.ws + OFF_ACTB) + idx;
;             float4 r = unpack_u2(rv[0][m][j]);
;             r.x += scale * acc[ai][0][m][0][j]; r.y += scale * acc[ai][0][m][1][j];
;             r.z += scale * acc[ai][1][m][0][j]; r.w += scale * acc[ai][1][m][1][j];
;             if (FINAL) {
;               acc[ai][0][m][0][j] = r.x; acc[ai][0][m][1][j] = r.y; acc[ai][1][m][0][j] = r.z; acc[ai][1][m][1][j] = r.w;
;             }
;             if (WRITE_B) __builtin_nontemporal_store(u32x2{pack2(r.x, r.y), pack2(r.z, r.w)}, (u32x2*)rp);
;             float ss = r.x * r.x + r.y * r.y + r.z * r.z + r.w * r.w;
;             ss = row16_sum(ss);
;             if (fr == 0) {
;               float* dstp = ssqg + (size_t)((mt * 4 + n) * 4 + wc) * 256 + row;
;               if (FINAL) __hip_atomic_store(dstp, ss, __ATOMIC_RELAXED, __HIP_MEMORY_SCOPE_AGENT);
;               else *dstp = ss;
.LBB0_156:
	s_or_b64 exec, exec, s[4:5]
	s_cmp_eq_u32 s1, 3
	s_cbranch_scc1 .Lpf5_skip
	s_add_i32 s4, s1, 1
	s_lshl_b32 s4, s4, 6
	s_add_i32 s4, s4, s71
	s_ashr_i32 s5, s4, 31
	s_lshl_b64 s[4:5], s[4:5], 21
	s_add_u32 s4, s33, s4
	s_addc_u32 s5, s96, s5
	s_and_b32 s5, s5, 0xffff
	s_mov_b32 s6, s10
	s_mov_b32 s7, s11
	s_mov_b32 m0, s37
	s_nop 0
	buffer_load_dwordx4 v250, s[8:11], 0 offen lds
	s_mov_b32 m0, s38
	s_nop 0
	buffer_load_dwordx4 v250, s[8:11], s16 offen lds
	s_mov_b32 m0, s36
	s_nop 0
	buffer_load_dwordx4 v250, s[4:7], 0 offen lds
	s_mov_b32 m0, s39
	s_nop 0
	buffer_load_dwordx4 v250, s[4:7], s16 offen lds
	s_mov_b32 m0, s40
	s_nop 0
	buffer_load_dwordx4 v250, s[8:11], s0 offen lds
	s_mov_b32 m0, s41
	s_nop 0
	buffer_load_dwordx4 v250, s[8:11], s17 offen lds
	s_mov_b32 m0, s42
	s_nop 0
	buffer_load_dwordx4 v250, s[4:7], s0 offen lds
	s_mov_b32 m0, s43
	s_nop 0
	buffer_load_dwordx4 v250, s[4:7], s17 offen lds
	s_mov_b32 m0, s45
	s_nop 0
	buffer_load_dwordx4 v250, s[8:11], s18 offen lds
	s_mov_b32 m0, s46
	s_nop 0
	buffer_load_dwordx4 v250, s[8:11], s19 offen lds
	s_mov_b32 m0, s47
	s_nop 0
	buffer_load_dwordx4 v250, s[4:7], s18 offen lds
	s_mov_b32 m0, s78
	s_nop 0
	buffer_load_dwordx4 v250, s[4:7], s19 offen lds
	s_mov_b32 m0, s82
	s_nop 0
	buffer_load_dwordx4 v250, s[8:11], s24 offen lds
	s_mov_b32 m0, s83
	s_nop 0
	buffer_load_dwordx4 v250, s[8:11], s25 offen lds
.Lpf5_skip:
	v_mov_b32_e32 v173, v170
	v_mov_b32_e32 v182, v169
	v_mov_b32_e32 v130, v171
	v_mov_b32_e32 v128, v168
	s_lshl_b64 s[6:7], s[14:15], 8
	v_lshlrev_b32_e32 v132, 6, v128
	v_ashrrev_i32_e32 v133, 31, v132
	v_lshlrev_b32_e32 v134, 2, v130
	v_lshl_add_u64 v[128:129], s[6:7], 0, v[132:133]
	v_ashrrev_i32_e32 v135, 31, v134
	v_lshl_add_u64 v[136:137], v[128:129], 0, v[134:135]
	v_lshlrev_b32_e32 v128, 6, v182
	v_ashrrev_i32_e32 v129, 31, v128
	v_lshlrev_b32_e32 v130, 2, v173
	v_ashrrev_i32_e32 v131, 31, v130
	v_lshlrev_b64 v[174:175], 1, v[128:129]
	v_lshl_add_u64 v[138:139], s[54:55], 0, v[174:175]
	v_lshlrev_b64 v[176:177], 1, v[130:131]
	v_lshl_add_u64 v[138:139], v[138:139], 0, v[176:177]
	v_lshlrev_b64 v[136:137], 11, v[136:137]
	v_lshl_add_u64 v[136:137], v[138:139], 0, v[136:137]
	v_add_co_u32_e32 v138, vcc, s27, v136
	s_mov_b32 s4, 0x8000
	s_nop 0
	v_addc_co_u32_e32 v139, vcc, 0, v137, vcc
	global_load_dwordx2 v[178:179], v[136:137], off
	global_load_dwordx2 v[166:167], v[136:137], off offset:2048
	global_load_dwordx2 v[164:165], v[138:139], off
	global_load_dwordx2 v[162:163], v[138:139], off offset:2048
	v_add_co_u32_e32 v138, vcc, s4, v136
	s_mov_b32 s4, 0x10000
	s_nop 0
	v_addc_co_u32_e32 v139, vcc, 0, v137, vcc
	v_add_co_u32_e32 v140, vcc, s31, v136
	v_add_u32_e32 v134, v134, v132
	s_nop 0
	v_addc_co_u32_e32 v141, vcc, 0, v137, vcc
	v_add_co_u32_e32 v142, vcc, s4, v136
	s_mov_b32 s4, 0x18000
	s_nop 0
	v_addc_co_u32_e32 v143, vcc, 0, v137, vcc
	v_add_co_u32_e32 v144, vcc, s34, v136
	v_ashrrev_i32_e32 v135, 31, v134
	s_nop 0
	v_addc_co_u32_e32 v145, vcc, 0, v137, vcc
	v_add_co_u32_e32 v146, vcc, s4, v136
	global_load_dwordx2 v[156:157], v[140:141], off
	global_load_dwordx2 v[154:155], v[140:141], off offset:2048
	global_load_dwordx2 v[152:153], v[144:145], off offset:-4096
	global_load_dwordx2 v[148:149], v[144:145], off
	v_addc_co_u32_e32 v147, vcc, 0, v137, vcc
	v_add_co_u32_e32 v180, vcc, s35, v136
	s_lshl_b32 s4, s14, 4
	s_nop 0
	v_addc_co_u32_e32 v181, vcc, 0, v137, vcc
	global_load_dwordx2 v[160:161], v[140:141], off offset:-4096
	global_load_dwordx2 v[158:159], v[138:139], off offset:2048
	global_load_dwordx2 v[150:151], v[142:143], off offset:2048
	s_nop 0
	global_load_dwordx2 v[142:143], v[146:147], off offset:2048
	s_nop 0
	global_load_dwordx2 v[146:147], v[144:145], off offset:2048
	s_nop 0
	global_load_dwordx2 v[144:145], v[180:181], off offset:-4096
	global_load_dwordx2 v[140:141], v[180:181], off
	global_load_dwordx2 v[138:139], v[180:181], off offset:2048
	s_or_b32 s14, s4, s76
	v_add_u32_e32 v180, s14, v182
	v_ashrrev_i32_e32 v181, 31, v180
	v_lshlrev_b64 v[132:133], 10, v[180:181]
	v_lshl_add_u64 v[180:181], s[6:7], 0, v[134:135]
	v_cmp_eq_u32_e64 s[4:5], 0, v173
	v_lshlrev_b64 v[180:181], 11, v[180:181]
	v_lshl_add_u64 v[180:181], s[54:55], 0, v[180:181]
	v_lshl_add_u64 v[174:175], v[180:181], 0, v[174:175]
	v_lshl_add_u64 v[132:133], s[50:51], 0, v[132:133]
	v_lshl_add_u64 v[174:175], v[174:175], 0, v[176:177]
	v_lshl_add_u64 v[132:133], v[134:135], 2, v[132:133]
	s_waitcnt vmcnt(15)
	v_lshlrev_b32_e32 v173, 16, v178
	v_and_b32_e32 v178, 0xffff0000, v178
	v_fmac_f32_e32 v178, 0.5, v116
	v_lshlrev_b32_e32 v180, 16, v179
	v_fmac_f32_e32 v173, 0.5, v112
	v_mul_f32_e32 v112, v178, v178
	v_and_b32_e32 v179, 0xffff0000, v179
	v_fmac_f32_e32 v180, 0.5, v120
	v_fmac_f32_e32 v112, v173, v173
	v_fmac_f32_e32 v179, 0.5, v124
	v_fmac_f32_e32 v112, v180, v180
	v_fmac_f32_e32 v112, v179, v179
	v_cvt_pk_bf16_f32 v176, v173, v178
	v_cvt_pk_bf16_f32 v177, v180, v179
	v_add_f32_dpp v112, v112, v112 quad_perm:[1,0,3,2] row_mask:0xf bank_mask:0xf bound_ctrl:1
	global_store_dwordx2 v[174:175], v[176:177], off nt
	s_nop 0
	v_add_f32_dpp v112, v112, v112 quad_perm:[2,3,0,1] row_mask:0xf bank_mask:0xf bound_ctrl:1
	s_nop 1
	v_add_f32_dpp v112, v112, v112 row_half_mirror row_mask:0xf bank_mask:0xf bound_ctrl:1
	s_nop 1
	v_mov_b32_dpp v116, v112 row_mirror row_mask:0xf bank_mask:0xf bound_ctrl:1
	s_and_saveexec_b64 s[14:15], s[4:5]
	s_cbranch_execz .LBB0_158
	v_add_f32_e32 v112, v112, v116
	global_store_dword v[132:133], v112, off
